# v32 + nt hint on the once-read key loads of the max|k| pass
# speedup vs baseline: 1.0062x; 1.0008x over previous
; __device__ __forceinline__ void phase2_kmax(const Params& p, int item) {
;     ...
;     for (int t = qr * 2052 + tid; t < (qr + 1) * 2052; t += 512) {
;         const bf16_t* kr = (const bf16_t*)(ws + R_QKV) + QKV_ONE / 2 + ((size_t)bh * TP + t) * 64;
;         float s1 = 0.f;
; #pragma unroll
;         for (int q = 0; q < 8; ++q) {
;             const u32x4 v = *(const u32x4*)(kr + q * 8);
; #pragma unroll
;             for (int e = 0; e < 4; ++e) { const float lo = __uint_as_float(v[e] << 16), hi = __uint_as_float(v[e] & 0xffff0000u); s1 += lo * lo + hi * hi; }
;         }
;         ss = fmaxf(ss, s1);
;     }
; #pragma unroll
;     for (int o = 1; o < 64; o <<= 1) ss = fmaxf(ss, __shfl_xor(ss, o));
;     __syncthreads();
;     if ((tid & 63) == 0) red[tid >> 6] = ss;
;     __syncthreads();
;     if (tid == 0) {
;         float m = red[0];
; #pragma unroll
;         for (int w = 1; w < 8; ++w) m = fmaxf(m, red[w]);
;         ((float*)(ws + WS_CTL))[16 + item] = m;
;     }
; }
.LBB0_765:
	global_load_dwordx4 v[12:15], v[2:3], off nt
	global_load_dwordx4 v[16:19], v[2:3], off offset:16 nt
	global_load_dwordx4 v[20:23], v[2:3], off offset:32 nt
	global_load_dwordx4 v[24:27], v[2:3], off offset:48 nt
	global_load_dwordx4 v[28:31], v[2:3], off offset:64 nt
	global_load_dwordx4 v[32:35], v[2:3], off offset:80 nt
	global_load_dwordx4 v[36:39], v[2:3], off offset:96 nt
	global_load_dwordx4 v[40:43], v[2:3], off offset:112 nt
	v_add_u32_e32 v10, 0x200, v10
	v_max_f32_e32 v0, v0, v0
	v_cmp_le_u32_e64 s[0:1], s11, v10
	v_lshl_add_u64 v[2:3], v[2:3], 0, s[4:5]
	s_or_b64 s[6:7], s[0:1], s[6:7]
	s_waitcnt vmcnt(7)
	v_and_b32_e32 v44, 0xffff0000, v12
	v_and_b32_e32 v46, 0xffff0000, v13
	v_lshlrev_b32_e32 v11, 16, v12
	v_lshlrev_b32_e32 v45, 16, v13
	v_and_b32_e32 v48, 0xffff0000, v14
	s_waitcnt vmcnt(5)
	v_lshlrev_b32_e32 v59, 16, v20
	v_and_b32_e32 v60, 0xffff0000, v20
	v_lshlrev_b32_e32 v61, 16, v21
	v_and_b32_e32 v62, 0xffff0000, v21
	v_lshlrev_b32_e32 v63, 16, v22
	v_and_b32_e32 v64, 0xffff0000, v22
	v_lshlrev_b32_e32 v65, 16, v23
	v_and_b32_e32 v66, 0xffff0000, v23
	s_waitcnt vmcnt(1)
	v_lshlrev_b32_e32 v21, 16, v37
	v_lshlrev_b32_e32 v20, 16, v36
	v_and_b32_e32 v23, 0xffff0000, v37
	v_and_b32_e32 v22, 0xffff0000, v36
	v_mul_f32_e32 v36, v44, v44
	v_mul_f32_e32 v37, v46, v46
	v_lshlrev_b32_e32 v47, 16, v14
	v_and_b32_e32 v50, 0xffff0000, v15
	v_lshlrev_b32_e32 v67, 16, v24
	v_and_b32_e32 v68, 0xffff0000, v24
	v_lshlrev_b32_e32 v71, 16, v26
	v_and_b32_e32 v72, 0xffff0000, v26
	v_lshlrev_b32_e32 v24, 16, v38
	v_and_b32_e32 v26, 0xffff0000, v38
	v_mul_f32_e32 v38, v48, v48
	v_fmac_f32_e32 v36, v11, v11
	v_fmac_f32_e32 v37, v45, v45
	v_lshlrev_b32_e32 v49, 16, v15
	v_and_b32_e32 v52, 0xffff0000, v16
	v_lshlrev_b32_e32 v69, 16, v25
	v_and_b32_e32 v70, 0xffff0000, v25
	v_lshlrev_b32_e32 v73, 16, v27
	v_and_b32_e32 v74, 0xffff0000, v27
	v_lshlrev_b32_e32 v25, 16, v39
	v_and_b32_e32 v27, 0xffff0000, v39
	v_mul_f32_e32 v39, v50, v50
	v_fmac_f32_e32 v38, v47, v47
	v_add_f32_e32 v11, v36, v37
	v_lshlrev_b32_e32 v51, 16, v16
	v_and_b32_e32 v54, 0xffff0000, v17
	v_lshlrev_b32_e32 v75, 16, v28
	v_and_b32_e32 v76, 0xffff0000, v28
	v_lshlrev_b32_e32 v79, 16, v30
	v_and_b32_e32 v80, 0xffff0000, v30
	s_waitcnt vmcnt(0)
	v_lshlrev_b32_e32 v28, 16, v40
	v_and_b32_e32 v30, 0xffff0000, v40
	v_mul_f32_e32 v40, v52, v52
	v_fmac_f32_e32 v39, v49, v49
	v_add_f32_e32 v11, v38, v11
	v_lshlrev_b32_e32 v53, 16, v17
	v_and_b32_e32 v56, 0xffff0000, v18
	v_lshlrev_b32_e32 v77, 16, v29
	v_and_b32_e32 v78, 0xffff0000, v29
	v_lshlrev_b32_e32 v81, 16, v31
	v_and_b32_e32 v82, 0xffff0000, v31
	v_lshlrev_b32_e32 v29, 16, v41
	v_and_b32_e32 v31, 0xffff0000, v41
	v_mul_f32_e32 v41, v54, v54
	v_fmac_f32_e32 v40, v51, v51
	v_add_f32_e32 v11, v39, v11
	v_lshlrev_b32_e32 v55, 16, v18
	v_and_b32_e32 v58, 0xffff0000, v19
	v_lshlrev_b32_e32 v12, 16, v32
	v_and_b32_e32 v14, 0xffff0000, v32
	v_lshlrev_b32_e32 v16, 16, v34
	v_and_b32_e32 v18, 0xffff0000, v34
	v_lshlrev_b32_e32 v32, 16, v42
	v_and_b32_e32 v34, 0xffff0000, v42
	v_mul_f32_e32 v42, v56, v56
	v_fmac_f32_e32 v41, v53, v53
	v_add_f32_e32 v11, v40, v11
	v_lshlrev_b32_e32 v57, 16, v19
	v_lshlrev_b32_e32 v13, 16, v33
	v_and_b32_e32 v15, 0xffff0000, v33
	v_lshlrev_b32_e32 v17, 16, v35
	v_and_b32_e32 v19, 0xffff0000, v35
	v_lshlrev_b32_e32 v33, 16, v43
	v_and_b32_e32 v35, 0xffff0000, v43
	v_mul_f32_e32 v43, v58, v58
	v_fmac_f32_e32 v42, v55, v55
	v_add_f32_e32 v11, v41, v11
	v_mul_f32_e32 v44, v60, v60
	v_fmac_f32_e32 v43, v57, v57
	v_add_f32_e32 v11, v42, v11
	v_mul_f32_e32 v46, v62, v62
	v_fmac_f32_e32 v44, v59, v59
	v_add_f32_e32 v11, v43, v11
	v_mul_f32_e32 v48, v64, v64
	v_fmac_f32_e32 v46, v61, v61
	v_add_f32_e32 v11, v44, v11
	v_mul_f32_e32 v50, v66, v66
	v_fmac_f32_e32 v48, v63, v63
	v_add_f32_e32 v11, v46, v11
	v_mul_f32_e32 v52, v68, v68
	v_fmac_f32_e32 v50, v65, v65
	v_add_f32_e32 v11, v48, v11
	v_mul_f32_e32 v54, v70, v70
	v_fmac_f32_e32 v52, v67, v67
	v_add_f32_e32 v11, v50, v11
	v_mul_f32_e32 v56, v72, v72
	v_fmac_f32_e32 v54, v69, v69
	v_add_f32_e32 v11, v52, v11
	v_mul_f32_e32 v58, v74, v74
	v_fmac_f32_e32 v56, v71, v71
	v_add_f32_e32 v11, v54, v11
	v_mul_f32_e32 v60, v76, v76
	v_fmac_f32_e32 v58, v73, v73
	v_add_f32_e32 v11, v56, v11
	v_mul_f32_e32 v62, v78, v78
	v_fmac_f32_e32 v60, v75, v75
	v_add_f32_e32 v11, v58, v11
	v_mul_f32_e32 v64, v80, v80
	v_fmac_f32_e32 v62, v77, v77
	v_add_f32_e32 v11, v60, v11
	v_mul_f32_e32 v66, v82, v82
	v_fmac_f32_e32 v64, v79, v79
	v_add_f32_e32 v11, v62, v11
	v_pk_mul_f32 v[14:15], v[14:15], v[14:15]
	v_fmac_f32_e32 v66, v81, v81
	v_add_f32_e32 v11, v64, v11
	v_pk_fma_f32 v[12:13], v[12:13], v[12:13], v[14:15]
	v_add_f32_e32 v11, v66, v11
	v_pk_mul_f32 v[18:19], v[18:19], v[18:19]
	v_add_f32_e32 v11, v12, v11
	v_pk_fma_f32 v[14:15], v[16:17], v[16:17], v[18:19]
	v_add_f32_e32 v11, v13, v11
	v_pk_mul_f32 v[22:23], v[22:23], v[22:23]
	v_add_f32_e32 v11, v14, v11
	v_pk_fma_f32 v[16:17], v[20:21], v[20:21], v[22:23]
	v_add_f32_e32 v11, v15, v11
	v_pk_mul_f32 v[26:27], v[26:27], v[26:27]
	v_add_f32_e32 v11, v16, v11
	v_pk_fma_f32 v[18:19], v[24:25], v[24:25], v[26:27]
	v_add_f32_e32 v11, v17, v11
	v_pk_mul_f32 v[30:31], v[30:31], v[30:31]
	v_add_f32_e32 v11, v18, v11
	v_pk_fma_f32 v[20:21], v[28:29], v[28:29], v[30:31]
	v_add_f32_e32 v11, v19, v11
	v_pk_mul_f32 v[34:35], v[34:35], v[34:35]
	v_add_f32_e32 v11, v20, v11
	v_pk_fma_f32 v[22:23], v[32:33], v[32:33], v[34:35]
	v_add_f32_e32 v11, v21, v11
	v_add_f32_e32 v11, v22, v11
	v_add_f32_e32 v11, v23, v11
	v_max_f32_e32 v0, v0, v11
	s_andn2_b64 exec, exec, s[6:7]
	s_cbranch_execnz .LBB0_765
	s_or_b64 exec, exec, s[6:7]
	ds_bpermute_b32 v2, v4, v0
	v_max_f32_e32 v0, v0, v0
	s_waitcnt lgkmcnt(0)
	s_barrier
	v_max_f32_e32 v2, v2, v2
	v_max_f32_e32 v0, v0, v2
	ds_bpermute_b32 v2, v5, v0
	s_waitcnt lgkmcnt(0)
	v_max_f32_e32 v2, v2, v2
	v_max_f32_e32 v0, v0, v2
	ds_bpermute_b32 v2, v6, v0
	s_waitcnt lgkmcnt(0)
	v_max_f32_e32 v2, v2, v2
	v_max_f32_e32 v0, v0, v2
	ds_bpermute_b32 v2, v7, v0
	s_waitcnt lgkmcnt(0)
	v_max_f32_e32 v2, v2, v2
	v_max_f32_e32 v0, v0, v2
	ds_bpermute_b32 v2, v8, v0
	s_waitcnt lgkmcnt(0)
	v_max_f32_e32 v2, v2, v2
	v_max_f32_e32 v0, v0, v2
	ds_bpermute_b32 v2, v9, v0
	s_and_saveexec_b64 s[0:1], vcc
	s_cbranch_execz .LBB0_768
	s_waitcnt lgkmcnt(0)
	v_max_f32_e32 v2, v2, v2
	v_max_f32_e32 v0, v0, v0
	v_max_f32_e32 v0, v0, v2
	v_add_u32_e32 v2, 0, v169
	v_add_u32_e32 v2, 0x19000, v2
	ds_write_b32 v2, v0
